# attention: the one static s_setprio raise moved from waves 0-3 to the younger half (waves 4-7)
# baseline (speedup 1.0000x reference)
; __global__ void __launch_bounds__(NTHR, 2) mega_fwd(Args a) {
;     ...
;         float* RSQ = (float*)(ws + WS_RSQ);
;         if (kind == 0) { if (KON(0))
;             prologue_phase(a, lds, tid, lane, wave);
;         } else if (kind == 1) { if (KON(1)) {
;             EpiSwiGLU E{BIG, ph == 1 ? (const float*)nullptr : (const float*)RSQ};
;             run_gemm(lds, XN, (const bf16*)(ws + WS_WGU + idx * WGU_STRIDE), 2 * DFF, DM, E); }
;         } else if (kind == 2 || kind == 10) { if (KON(2)) {
;             const bool dn = kind == 2;
;             const float* gn = ph == 2 ? a.in[5] : (ph == 9 ? a.in[1] + DM : (ph == 11 ? a.in[1] + 2 * DM : (ph == 13 ? a.in[5] + DM : (ph == 17 ? a.in[1] + 3 * DM : (const float*)nullptr))));
;             EpiResid E{ph == 2 ? a.in[0] : (const float*)X, X, gn, XN, RSQ, dn ? 0.5f : 1.0f, 0.f};
;             const bf16* A = dn ? (const bf16*)BIG : (idx == 0 ? (const bf16*)(ws + WS_R1) : (const bf16*)BIG);
;             const bf16* Bt = dn ? (const bf16*)(ws + WS_WD + idx * WD_STRIDE) : (const bf16*)(ws + (idx == 0 ? WS_WEOUT : WS_WCOUT));
;             run_gemm(lds, A, Bt, DM, dn ? DFF : DM, E); }
;         } else if (kind == 4) { if (KON(4)) {
;             EpiStore E{BIG, idx == 0 ? ZW : Z3W, (const float*)RSQ};
;             run_gemm(lds, XN, (const bf16*)(ws + (idx == 0 ? WS_WAIN : WS_WCIN)), idx == 0 ? ZW : Z3W, DM, E); }
;         } else if (kind == 5) { if (KON(5))
;             e1_phase(BIG, a.in[7], (bf16*)(ws + WS_LRIN), tid);
;         } else if (kind == 6) { if (KON(6)) {
;             EpiLowRank E{(float*)(ws + WS_R1), (bf16*)(ws + WS_R2), (bf16*)(ws + WS_R4), a.in[8], a.in[10]};
;             run_gemm(lds, (const bf16*)(ws + WS_LRIN), (const bf16*)(ws + WS_WBD), 1536, 256, E); }
;         } else if (kind == 7) { if (KON(7))
;             e2_phase(a, BIG, (bf16*)(ws + WS_R2), (float*)(ws + WS_R1), (bf16*)(ws + WS_R3), (float*)(ws + WS_BON), gw, NGW, lane);
;         } else if (kind == 8) { if (KON(8))
;             scan_phase(a, lds, BIG, (const float*)(ws + WS_R1), (const bf16*)(ws + WS_R2), (const bf16*)(ws + WS_R3), (float*)(ws + WS_XN), tid, lane, wave);
;         } else if (kind == 9) { if (KON(9))
;             e3_phase(a, lds, BIG, (const float*)(ws + WS_XN), (const float*)(ws + WS_BON), (const bf16*)(ws + WS_R4), (bf16*)(ws + WS_R1), tid, lane, wave);
;         } else if (kind == 11) { if (KON(11))
.LBB0_82:
	v_readlane_b32 s2, v252, 4
	v_and_b32_e32 v245, 63, v216
	s_andn2_b64 vcc, exec, s[14:15]
	s_add_i32 s40, s96, s2
	s_cbranch_vccnz .LBB0_652
	s_load_dwordx16 s[52:67], s[0:1], 0xd8
	s_ashr_i32 s5, s4, 31
	s_mov_b64 s[8:9], -1
	s_waitcnt lgkmcnt(0)
	s_add_u32 s90, s66, s4
	s_addc_u32 s91, s67, s5
	s_add_u32 s14, s90, 0x5800000
	s_addc_u32 s15, s91, 0
	s_add_u32 s28, s90, 0x9800000
	s_addc_u32 s29, s91, 0
	s_add_u32 s88, s90, 0x5600000
	s_addc_u32 s89, s91, 0
	s_andn2_b64 vcc, exec, s[12:13]
	s_cbranch_vccz .LBB0_626
	s_or_b64 s[8:9], s[78:79], s[16:17]
	v_writelane_b32 v254, s73, 52
	s_andn2_b64 vcc, exec, s[8:9]
	s_mov_b64 s[8:9], -1
	s_cbranch_vccz .LBB0_528
	s_xor_b64 s[12:13], s[20:21], -1
	s_and_b64 vcc, exec, s[12:13]
	s_cbranch_vccz .LBB0_505
	s_xor_b64 s[12:13], s[48:49], -1
	s_and_b64 vcc, exec, s[12:13]
	s_cbranch_vccz .LBB0_482
	v_writelane_b32 v254, s86, 53
	s_xor_b64 s[12:13], s[46:47], -1
	s_and_b64 vcc, exec, s[12:13]
	v_writelane_b32 v254, s87, 54
	v_writelane_b32 v254, s88, 55
	s_nop 1
	v_writelane_b32 v254, s89, 56
	v_writelane_b32 v254, s90, 57
	s_nop 1
	v_writelane_b32 v254, s91, 58
	v_writelane_b32 v254, s78, 59
	s_nop 1
	v_writelane_b32 v254, s79, 60
	s_cbranch_vccz .LBB0_324
	s_xor_b64 s[12:13], s[44:45], -1
	s_and_b64 vcc, exec, s[12:13]
	s_cbranch_vccz .LBB0_307
	s_xor_b64 s[12:13], s[42:43], -1
	s_and_b64 vcc, exec, s[12:13]
	s_cbranch_vccz .LBB0_194
	s_xor_b64 s[8:9], s[6:7], -1
	s_mov_b64 s[6:7], -1
	s_and_b64 vcc, exec, s[8:9]
	s_cbranch_vccz .LBB0_150
	s_xor_b64 s[8:9], s[10:11], -1
	s_add_u32 s10, s90, 0x15800000
	s_addc_u32 s11, s91, 0
	s_add_u32 s46, s90, 0x19800000
	s_addc_u32 s47, s91, 0
	s_and_b64 vcc, exec, s[8:9]
	s_cbranch_vccz .LBB0_138
	v_readlane_b32 s6, v252, 14
	v_readlane_b32 s7, v252, 15
	s_cmp_gt_i32 s96, 3
	s_nop 3
	global_load_dword v156, v1, s[6:7]
	s_cbranch_scc0 .LBB0_94
	s_setprio 2
